# idle waves prefetch the next GEMM phase's first weight K-tiles into L2 during the grid barrier
# baseline (speedup 1.0000x reference)
; __device__ __forceinline__ unsigned xb_ld(unsigned* p)              { return __hip_atomic_load(p, __ATOMIC_RELAXED, __HIP_MEMORY_SCOPE_AGENT); }
; __device__ __forceinline__ void xcd_barrier_complete(unsigned* bar, unsigned x, unsigned& nloc, unsigned& nx) {
;     const unsigned G = gridDim.x * gridDim.y * gridDim.z;
;     unsigned sum, cnt, mine, sp = 0u;
;     for (;;) {
;         sum = 0u; cnt = 0u; mine = 0u;
; #pragma unroll
;         for (unsigned j = 0; j < 16; ++j) { const unsigned c = xb_ld(&bar[XB_XCNT(j)]); sum += c; cnt += (c > 0u) ? 1u : 0u; mine = (j == x) ? c : mine; }
; __device__ __forceinline__ void xcd_barrier(const XcdBarrier& b) {
;     asm volatile("s_waitcnt vmcnt(0)" ::: "memory");
;     __syncthreads();
;     if (threadIdx.x == 0) {
;         unsigned* bar = b.bar;
;         __builtin_amdgcn_s_waitcnt(0);
;         unsigned nloc = b.st[0], nx = b.st[1];
;         if (nloc == 0u) { xcd_barrier_complete(bar, b.x, nloc, nx); b.st[0] = nloc; b.st[1] = nx; }
.LBB0_174:
	s_cmp_gt_i32 s29, 2
	s_cselect_b64 s[4:5], -1, 0
	s_and_b64 s[2:3], s[6:7], s[4:5]
	s_andn2_b64 vcc, exec, s[2:3]
	s_cbranch_vccnz .LBB0_224
	s_waitcnt vmcnt(0)
	v_cmp_eq_u32_e32 vcc, 0, v0
	s_barrier
	v_readfirstlane_b32 s101, v0
	v_readlane_b32 s98, v244, 9
	v_readlane_b32 s99, v244, 10
	v_readlane_b32 s100, v244, 60
	s_cmp_lt_u32 s101, 64
	s_cbranch_scc1 .Lwpf_skip_1
	s_lshr_b32 s100, s100, 6
	s_mul_i32 s100, s100, 0x100000
	s_add_u32 s98, s98, 0x2100000
	s_addc_u32 s99, s99, 0
	s_add_u32 s98, s98, s100
	s_addc_u32 s99, s99, 0
	v_subrev_u32_e32 v250, 64, v0
	v_lshrrev_b32_e32 v252, 2, v250
	v_and_b32_e32 v251, 3, v250
	v_mul_u32_u24_e32 v252, 0x1000, v252
	v_lshl_add_u32 v252, v251, 7, v252
	global_load_dword v253, v252, s[98:99]
	v_add_u32_e32 v251, 448, v250
	v_lshrrev_b32_e32 v252, 2, v251
	v_and_b32_e32 v251, 3, v251
	v_mul_u32_u24_e32 v252, 0x1000, v252
	v_lshl_add_u32 v252, v251, 7, v252
	global_load_dword v254, v252, s[98:99]
	v_add_u32_e32 v251, 896, v250
	v_min_u32_e32 v251, 0x3ff, v251
	v_lshrrev_b32_e32 v252, 2, v251
	v_and_b32_e32 v251, 3, v251
	v_mul_u32_u24_e32 v252, 0x1000, v252
	v_lshl_add_u32 v252, v251, 7, v252
	global_load_dword v255, v252, s[98:99]
.Lwpf_skip_1:
	s_and_saveexec_b64 s[6:7], vcc
	s_cbranch_execz .LBB0_223
	v_mov_b32_e32 v1, s31
	s_waitcnt vmcnt(0) expcnt(0) lgkmcnt(0)
	ds_read_b32 v3, v1
	ds_read_b32 v1, v1 offset:4
	s_waitcnt lgkmcnt(1)
	v_cmp_ne_u32_e32 vcc, 0, v3
	s_cbranch_vccnz .LBB0_191
	v_readlane_b32 s8, v244, 0
	v_readlane_b32 s9, v244, 1
	s_load_dwordx2 s[2:3], s[8:9], 0x4
	s_load_dwordx8 s[20:27], s[0:1], 0x100
	s_load_dword s12, s[0:1], 0x130
	s_mov_b32 s48, s97
	v_mov_b32_e32 v17, 0
	s_waitcnt lgkmcnt(0)
	s_add_u32 s8, s26, 0x4200
	s_addc_u32 s9, s27, 0
	s_add_u32 s10, s26, 0x4400
	s_addc_u32 s11, s27, 0
	s_mul_i32 s2, s2, s12
	s_add_u32 s12, s26, 0x4500
	s_addc_u32 s13, s27, 0
	s_add_u32 s14, s26, 0x4600
	s_addc_u32 s15, s27, 0
	s_add_u32 s16, s26, 0x4700
	s_addc_u32 s17, s27, 0
	s_add_u32 s18, s26, 0x4800
	s_addc_u32 s19, s27, 0
	s_add_u32 s20, s26, 0x4900
	s_addc_u32 s21, s27, 0
	s_add_u32 s22, s26, 0x4a00
	s_addc_u32 s23, s27, 0
	s_add_u32 s34, s26, 0x4b00
	s_addc_u32 s35, s27, 0
	s_add_u32 s84, s26, 0x4c00
	s_addc_u32 s85, s27, 0
	s_add_u32 s86, s26, 0x4d00
	s_addc_u32 s87, s27, 0
	s_add_u32 s88, s26, 0x4e00
	s_addc_u32 s89, s27, 0
	s_add_u32 s92, s26, 0x4f00
	s_addc_u32 s93, s27, 0
	s_add_u32 s96, s26, 0x5000
	s_addc_u32 s97, s27, 0
	s_add_u32 s36, s26, 0x5100
	s_addc_u32 s37, s27, 0
	s_add_u32 s38, s26, 0x5200
	s_addc_u32 s39, s27, 0
	s_add_u32 s40, s26, 0x5300
	s_mul_i32 s2, s2, s3
	s_addc_u32 s41, s27, 0
	s_mov_b32 s3, 1
	s_branch .LBB0_179

; __device__ __forceinline__ unsigned xb_ld(unsigned* p)              { return __hip_atomic_load(p, __ATOMIC_RELAXED, __HIP_MEMORY_SCOPE_AGENT); }
; __device__ __forceinline__ void xcd_barrier_complete(unsigned* bar, unsigned x, unsigned& nloc, unsigned& nx) {
;     const unsigned G = gridDim.x * gridDim.y * gridDim.z;
;     unsigned sum, cnt, mine, sp = 0u;
;     for (;;) {
;         sum = 0u; cnt = 0u; mine = 0u;
; #pragma unroll
;         for (unsigned j = 0; j < 16; ++j) { const unsigned c = xb_ld(&bar[XB_XCNT(j)]); sum += c; cnt += (c > 0u) ? 1u : 0u; mine = (j == x) ? c : mine; }
; __device__ __forceinline__ void xcd_barrier(const XcdBarrier& b) {
;     asm volatile("s_waitcnt vmcnt(0)" ::: "memory");
;     __syncthreads();
;     if (threadIdx.x == 0) {
;         unsigned* bar = b.bar;
;         __builtin_amdgcn_s_waitcnt(0);
;         unsigned nloc = b.st[0], nx = b.st[1];
;         if (nloc == 0u) { xcd_barrier_complete(bar, b.x, nloc, nx); b.st[0] = nloc; b.st[1] = nx; }
.LBB0_314:
	s_cmp_gt_i32 s29, 3
	s_cselect_b64 s[4:5], -1, 0
	s_and_b64 s[2:3], s[8:9], s[4:5]
	s_andn2_b64 vcc, exec, s[2:3]
	v_writelane_b32 v243, s31, 5
	s_cbranch_vccnz .LBB0_364
	s_waitcnt vmcnt(0)
	v_cmp_eq_u32_e32 vcc, 0, v0
	s_barrier
	v_readfirstlane_b32 s101, v0
	v_readlane_b32 s98, v244, 9
	v_readlane_b32 s99, v244, 10
	v_readlane_b32 s100, v244, 60
	s_cmp_lt_u32 s101, 64
	s_cbranch_scc1 .Lwpf_skip_2
	s_lshr_b32 s100, s100, 6
	s_mul_i32 s100, s100, 0x80000
	s_add_u32 s98, s98, 0x3100000
	s_addc_u32 s99, s99, 0
	s_add_u32 s98, s98, s100
	s_addc_u32 s99, s99, 0
	v_subrev_u32_e32 v250, 64, v0
	v_lshrrev_b32_e32 v252, 2, v250
	v_and_b32_e32 v251, 3, v250
	v_mul_u32_u24_e32 v252, 0x800, v252
	v_lshl_add_u32 v252, v251, 7, v252
	global_load_dword v253, v252, s[98:99]
	v_add_u32_e32 v251, 448, v250
	v_lshrrev_b32_e32 v252, 2, v251
	v_and_b32_e32 v251, 3, v251
	v_mul_u32_u24_e32 v252, 0x800, v252
	v_lshl_add_u32 v252, v251, 7, v252
	global_load_dword v254, v252, s[98:99]
	v_add_u32_e32 v251, 896, v250
	v_min_u32_e32 v251, 0x3ff, v251
	v_lshrrev_b32_e32 v252, 2, v251
	v_and_b32_e32 v251, 3, v251
	v_mul_u32_u24_e32 v252, 0x800, v252
	v_lshl_add_u32 v252, v251, 7, v252
	global_load_dword v255, v252, s[98:99]
.Lwpf_skip_2:
	s_and_saveexec_b64 s[6:7], vcc
	s_cbranch_execz .LBB0_363
	v_mov_b32_e32 v1, s31
	s_waitcnt vmcnt(0) expcnt(0) lgkmcnt(0)
	ds_read_b32 v3, v1
	ds_read_b32 v1, v1 offset:4
	s_waitcnt lgkmcnt(1)
	v_cmp_ne_u32_e32 vcc, 0, v3
	s_cbranch_vccnz .LBB0_331
	v_readlane_b32 s8, v244, 0
	v_readlane_b32 s9, v244, 1
	s_load_dwordx2 s[2:3], s[8:9], 0x4
	s_load_dwordx8 s[20:27], s[0:1], 0x100
	s_load_dword s12, s[0:1], 0x130
	v_mov_b32_e32 v17, 0
	s_waitcnt lgkmcnt(0)
	s_add_u32 s8, s26, 0x4200
	s_addc_u32 s9, s27, 0
	s_add_u32 s10, s26, 0x4400
	s_addc_u32 s11, s27, 0
	s_mul_i32 s2, s2, s12
	s_add_u32 s12, s26, 0x4500
	s_addc_u32 s13, s27, 0
	s_add_u32 s14, s26, 0x4600
	s_addc_u32 s15, s27, 0
	s_add_u32 s16, s26, 0x4700
	s_addc_u32 s17, s27, 0
	s_add_u32 s18, s26, 0x4800
	s_addc_u32 s19, s27, 0
	s_add_u32 s20, s26, 0x4900
	s_addc_u32 s21, s27, 0
	s_add_u32 s22, s26, 0x4a00
	s_addc_u32 s23, s27, 0
	s_add_u32 s34, s26, 0x4b00
	s_addc_u32 s35, s27, 0
	s_add_u32 s68, s26, 0x4c00
	s_addc_u32 s69, s27, 0
	s_add_u32 s70, s26, 0x4d00
	s_addc_u32 s71, s27, 0
	s_add_u32 s84, s26, 0x4e00
	s_addc_u32 s85, s27, 0
	s_add_u32 s86, s26, 0x4f00
	s_addc_u32 s87, s27, 0
	s_add_u32 s88, s26, 0x5000
	s_addc_u32 s89, s27, 0
	s_add_u32 s36, s26, 0x5100
	s_addc_u32 s37, s27, 0
	s_add_u32 s38, s26, 0x5200
	s_addc_u32 s39, s27, 0
	s_add_u32 s40, s26, 0x5300
	s_mul_i32 s2, s2, s3
	s_addc_u32 s41, s27, 0
	s_mov_b32 s3, 1
	s_branch .LBB0_319

; __device__ __forceinline__ unsigned xb_ld(unsigned* p)              { return __hip_atomic_load(p, __ATOMIC_RELAXED, __HIP_MEMORY_SCOPE_AGENT); }
; __device__ __forceinline__ void xcd_barrier_complete(unsigned* bar, unsigned x, unsigned& nloc, unsigned& nx) {
;     const unsigned G = gridDim.x * gridDim.y * gridDim.z;
;     unsigned sum, cnt, mine, sp = 0u;
;     for (;;) {
;         sum = 0u; cnt = 0u; mine = 0u;
; #pragma unroll
;         for (unsigned j = 0; j < 16; ++j) { const unsigned c = xb_ld(&bar[XB_XCNT(j)]); sum += c; cnt += (c > 0u) ? 1u : 0u; mine = (j == x) ? c : mine; }
; __device__ __forceinline__ void xcd_barrier(const XcdBarrier& b) {
;     asm volatile("s_waitcnt vmcnt(0)" ::: "memory");
;     __syncthreads();
;     if (threadIdx.x == 0) {
;         unsigned* bar = b.bar;
;         __builtin_amdgcn_s_waitcnt(0);
;         unsigned nloc = b.st[0], nx = b.st[1];
;         if (nloc == 0u) { xcd_barrier_complete(bar, b.x, nloc, nx); b.st[0] = nloc; b.st[1] = nx; }
.LBB0_878:
	s_cmp_gt_i32 s29, 8
	s_cselect_b64 s[0:1], -1, 0
	s_and_b64 s[2:3], s[6:7], s[0:1]
	s_andn2_b64 vcc, exec, s[2:3]
	s_cbranch_vccnz .LBB0_928
	s_waitcnt vmcnt(0)
	v_cmp_eq_u32_e32 vcc, 0, v0
	s_waitcnt vmcnt(0) lgkmcnt(0)
	s_barrier
	v_readfirstlane_b32 s101, v0
	v_readlane_b32 s98, v244, 9
	v_readlane_b32 s99, v244, 10
	v_readlane_b32 s100, v244, 60
	s_cmp_lt_u32 s101, 64
	s_cbranch_scc1 .Lwpf_skip_6
	s_lshr_b32 s100, s100, 6
	s_mul_i32 s100, s100, 0x80000
	s_add_u32 s98, s98, 0x900000
	s_addc_u32 s99, s99, 0
	s_add_u32 s98, s98, s100
	s_addc_u32 s99, s99, 0
	v_subrev_u32_e32 v250, 64, v0
	v_lshrrev_b32_e32 v252, 2, v250
	v_and_b32_e32 v251, 3, v250
	v_mul_u32_u24_e32 v252, 0x800, v252
	v_lshl_add_u32 v252, v251, 7, v252
	global_load_dword v253, v252, s[98:99]
	v_add_u32_e32 v251, 448, v250
	v_lshrrev_b32_e32 v252, 2, v251
	v_and_b32_e32 v251, 3, v251
	v_mul_u32_u24_e32 v252, 0x800, v252
	v_lshl_add_u32 v252, v251, 7, v252
	global_load_dword v254, v252, s[98:99]
	v_add_u32_e32 v251, 896, v250
	v_min_u32_e32 v251, 0x3ff, v251
	v_lshrrev_b32_e32 v252, 2, v251
	v_and_b32_e32 v251, 3, v251
	v_mul_u32_u24_e32 v252, 0x800, v252
	v_lshl_add_u32 v252, v251, 7, v252
	global_load_dword v255, v252, s[98:99]
.Lwpf_skip_6:
	s_and_saveexec_b64 s[4:5], vcc
	s_cbranch_execz .LBB0_927
	v_readlane_b32 s2, v243, 5
	s_waitcnt vmcnt(0) expcnt(0) lgkmcnt(0)
	s_nop 0
	v_mov_b32_e32 v1, s2
	ds_read_b32 v3, v1
	ds_read_b32 v1, v1 offset:4
	s_waitcnt lgkmcnt(1)
	v_cmp_ne_u32_e32 vcc, 0, v3
	s_cbranch_vccnz .LBB0_895
	v_readlane_b32 s6, v244, 0
	v_readlane_b32 s7, v244, 1
	v_readlane_b32 s20, v244, 3
	s_load_dwordx2 s[2:3], s[6:7], 0x4
	v_readlane_b32 s26, v244, 9
	v_readlane_b32 s27, v244, 10
	s_add_u32 s6, s26, 0x4200
	s_addc_u32 s7, s27, 0
	s_add_u32 s8, s26, 0x4400
	s_addc_u32 s9, s27, 0
	v_readlane_b32 s10, v244, 2
	s_waitcnt lgkmcnt(0)
	s_mul_i32 s2, s2, s10
	s_add_u32 s10, s26, 0x4500
	s_addc_u32 s11, s27, 0
	s_add_u32 s12, s26, 0x4600
	s_addc_u32 s13, s27, 0
	s_add_u32 s14, s26, 0x4700
	s_addc_u32 s15, s27, 0
	s_add_u32 s16, s26, 0x4800
	s_addc_u32 s17, s27, 0
	s_add_u32 s18, s26, 0x4900
	s_addc_u32 s19, s27, 0
	v_readlane_b32 s21, v244, 4
	s_add_u32 s20, s26, 0x4a00
	v_readlane_b32 s22, v244, 5
	s_addc_u32 s21, s27, 0
	v_readlane_b32 s23, v244, 6
	s_add_u32 s22, s26, 0x4b00
	s_addc_u32 s23, s27, 0
	s_add_u32 s34, s26, 0x4c00
	s_addc_u32 s35, s27, 0
	s_add_u32 s36, s26, 0x4d00
	s_addc_u32 s37, s27, 0
	s_add_u32 s38, s26, 0x4e00
	s_addc_u32 s39, s27, 0
	s_add_u32 s40, s26, 0x4f00
	s_addc_u32 s41, s27, 0
	s_add_u32 s56, s26, 0x5000
	s_addc_u32 s57, s27, 0
	s_add_u32 s42, s26, 0x5100
	s_addc_u32 s43, s27, 0
	s_add_u32 s44, s26, 0x5200
	s_addc_u32 s45, s27, 0
	s_add_u32 s46, s26, 0x5300
	s_mul_i32 s2, s2, s3
	s_addc_u32 s47, s27, 0
	s_mov_b32 s3, 1
	v_mov_b32_e32 v17, 0
	v_readlane_b32 s24, v244, 7
	v_readlane_b32 s25, v244, 8
	s_branch .LBB0_883

; __device__ __forceinline__ void xcd_barrier(const XcdBarrier& b) {
;     asm volatile("s_waitcnt vmcnt(0)" ::: "memory");
;     __syncthreads();
;     if (threadIdx.x == 0) {
.LBB0_968:
	s_cmp_gt_i32 s29, 9
	s_cselect_b64 s[0:1], -1, 0
	s_and_b64 s[2:3], s[4:5], s[0:1]
	s_andn2_b64 vcc, exec, s[2:3]
	s_cbranch_vccnz .LBB0_1018
	s_waitcnt vmcnt(0)
	v_cmp_eq_u32_e32 vcc, 0, v0
	s_waitcnt vmcnt(0) lgkmcnt(0)
	s_barrier
	v_readfirstlane_b32 s101, v0
	v_readlane_b32 s98, v244, 9
	v_readlane_b32 s99, v244, 10
	v_readlane_b32 s100, v244, 60
	s_cmp_lt_u32 s101, 64
	s_cbranch_scc1 .Lwpf_skip_7
	s_lshr_b32 s100, s100, 6
	s_mul_i32 s100, s100, 0x100000
	s_add_u32 s98, s98, 0x2500000
	s_addc_u32 s99, s99, 0
	s_add_u32 s98, s98, s100
	s_addc_u32 s99, s99, 0
	v_subrev_u32_e32 v250, 64, v0
	v_lshrrev_b32_e32 v252, 2, v250
	v_and_b32_e32 v251, 3, v250
	v_mul_u32_u24_e32 v252, 0x1000, v252
	v_lshl_add_u32 v252, v251, 7, v252
	global_load_dword v253, v252, s[98:99]
	v_add_u32_e32 v251, 448, v250
	v_lshrrev_b32_e32 v252, 2, v251
	v_and_b32_e32 v251, 3, v251
	v_mul_u32_u24_e32 v252, 0x1000, v252
	v_lshl_add_u32 v252, v251, 7, v252
	global_load_dword v254, v252, s[98:99]
	v_add_u32_e32 v251, 896, v250
	v_min_u32_e32 v251, 0x3ff, v251
	v_lshrrev_b32_e32 v252, 2, v251
	v_and_b32_e32 v251, 3, v251
	v_mul_u32_u24_e32 v252, 0x1000, v252
	v_lshl_add_u32 v252, v251, 7, v252
	global_load_dword v255, v252, s[98:99]

; __device__ __forceinline__ void xcd_barrier(const XcdBarrier& b) {
;     asm volatile("s_waitcnt vmcnt(0)" ::: "memory");
;     __syncthreads();
;     if (threadIdx.x == 0) {
.LBB0_1108:
	s_cmp_gt_i32 s29, 10
	s_cselect_b64 s[0:1], -1, 0
	s_and_b64 s[2:3], s[6:7], s[0:1]
	s_andn2_b64 vcc, exec, s[2:3]
	s_cbranch_vccnz .LBB0_1158
	s_waitcnt vmcnt(0)
	v_cmp_eq_u32_e32 vcc, 0, v0
	s_waitcnt vmcnt(0) lgkmcnt(0)
	s_barrier
	v_readfirstlane_b32 s101, v0
	v_readlane_b32 s98, v244, 9
	v_readlane_b32 s99, v244, 10
	v_readlane_b32 s100, v244, 60
	s_cmp_lt_u32 s101, 64
	s_cbranch_scc1 .Lwpf_skip_8
	s_lshr_b32 s100, s100, 6
	s_mul_i32 s100, s100, 0x80000
	s_add_u32 s98, s98, 0x1100000
	s_addc_u32 s99, s99, 0
	s_add_u32 s98, s98, s100
	s_addc_u32 s99, s99, 0
	v_subrev_u32_e32 v250, 64, v0
	v_lshrrev_b32_e32 v252, 2, v250
	v_and_b32_e32 v251, 3, v250
	v_mul_u32_u24_e32 v252, 0x800, v252
	v_lshl_add_u32 v252, v251, 7, v252
	global_load_dword v253, v252, s[98:99]
	v_add_u32_e32 v251, 448, v250
	v_lshrrev_b32_e32 v252, 2, v251
	v_and_b32_e32 v251, 3, v251
	v_mul_u32_u24_e32 v252, 0x800, v252
	v_lshl_add_u32 v252, v251, 7, v252
	global_load_dword v254, v252, s[98:99]
	v_add_u32_e32 v251, 896, v250
	v_min_u32_e32 v251, 0x3ff, v251
	v_lshrrev_b32_e32 v252, 2, v251
	v_and_b32_e32 v251, 3, v251
	v_mul_u32_u24_e32 v252, 0x800, v252
	v_lshl_add_u32 v252, v251, 7, v252
	global_load_dword v255, v252, s[98:99]

; __device__ __forceinline__ void xcd_barrier(const XcdBarrier& b) {
;     asm volatile("s_waitcnt vmcnt(0)" ::: "memory");
;     __syncthreads();
;     if (threadIdx.x == 0) {
.LBB0_1198:
	s_cmp_gt_i32 s29, 11
	s_cselect_b64 s[0:1], -1, 0
	s_and_b64 s[2:3], s[4:5], s[0:1]
	s_andn2_b64 vcc, exec, s[2:3]
	s_cbranch_vccnz .LBB0_1248
	s_waitcnt vmcnt(0)
	v_cmp_eq_u32_e32 vcc, 0, v0
	s_waitcnt vmcnt(0) lgkmcnt(0)
	s_barrier
	v_readfirstlane_b32 s101, v0
	v_readlane_b32 s98, v244, 9
	v_readlane_b32 s99, v244, 10
	v_readlane_b32 s100, v244, 60
	s_cmp_lt_u32 s101, 64
	s_cbranch_scc1 .Lwpf_skip_9
	s_lshr_b32 s100, s100, 6
	s_mul_i32 s100, s100, 0x100000
	s_add_u32 s98, s98, 0x2900000
	s_addc_u32 s99, s99, 0
	s_add_u32 s98, s98, s100
	s_addc_u32 s99, s99, 0
	v_subrev_u32_e32 v250, 64, v0
	v_lshrrev_b32_e32 v252, 2, v250
	v_and_b32_e32 v251, 3, v250
	v_mul_u32_u24_e32 v252, 0x1000, v252
	v_lshl_add_u32 v252, v251, 7, v252
	global_load_dword v253, v252, s[98:99]
	v_add_u32_e32 v251, 448, v250
	v_lshrrev_b32_e32 v252, 2, v251
	v_and_b32_e32 v251, 3, v251
	v_mul_u32_u24_e32 v252, 0x1000, v252
	v_lshl_add_u32 v252, v251, 7, v252
	global_load_dword v254, v252, s[98:99]
	v_add_u32_e32 v251, 896, v250
	v_min_u32_e32 v251, 0x3ff, v251
	v_lshrrev_b32_e32 v252, 2, v251
	v_and_b32_e32 v251, 3, v251
	v_mul_u32_u24_e32 v252, 0x1000, v252
	v_lshl_add_u32 v252, v251, 7, v252
	global_load_dword v255, v252, s[98:99]

; __device__ __forceinline__ void xcd_barrier(const XcdBarrier& b) {
;     asm volatile("s_waitcnt vmcnt(0)" ::: "memory");
;     __syncthreads();
;     if (threadIdx.x == 0) {
.LBB0_1338:
	s_cmp_gt_i32 s29, 12
	s_cselect_b64 s[0:1], -1, 0
	s_and_b64 s[2:3], s[6:7], s[0:1]
	s_andn2_b64 vcc, exec, s[2:3]
	s_cbranch_vccnz .LBB0_1388
	s_waitcnt vmcnt(0)
	v_cmp_eq_u32_e32 vcc, 0, v0
	s_waitcnt vmcnt(0) lgkmcnt(0)
	s_barrier
	v_readfirstlane_b32 s101, v0
	v_readlane_b32 s98, v244, 9
	v_readlane_b32 s99, v244, 10
	v_readlane_b32 s100, v244, 60
	s_cmp_lt_u32 s101, 64
	s_cbranch_scc1 .Lwpf_skip_10
	s_lshr_b32 s100, s100, 6
	s_mul_i32 s100, s100, 0x80000
	s_add_u32 s98, s98, 0x3800000
	s_addc_u32 s99, s99, 0
	s_add_u32 s98, s98, s100
	s_addc_u32 s99, s99, 0
	v_subrev_u32_e32 v250, 64, v0
	v_lshrrev_b32_e32 v252, 2, v250
	v_and_b32_e32 v251, 3, v250
	v_mul_u32_u24_e32 v252, 0x800, v252
	v_lshl_add_u32 v252, v251, 7, v252
	global_load_dword v253, v252, s[98:99]
	v_add_u32_e32 v251, 448, v250
	v_lshrrev_b32_e32 v252, 2, v251
	v_and_b32_e32 v251, 3, v251
	v_mul_u32_u24_e32 v252, 0x800, v252
	v_lshl_add_u32 v252, v251, 7, v252
	global_load_dword v254, v252, s[98:99]
	v_add_u32_e32 v251, 896, v250
	v_min_u32_e32 v251, 0x3ff, v251
	v_lshrrev_b32_e32 v252, 2, v251
	v_and_b32_e32 v251, 3, v251
	v_mul_u32_u24_e32 v252, 0x800, v252
	v_lshl_add_u32 v252, v251, 7, v252
	global_load_dword v255, v252, s[98:99]

; __device__ __forceinline__ unsigned xb_ld(unsigned* p)              { return __hip_atomic_load(p, __ATOMIC_RELAXED, __HIP_MEMORY_SCOPE_AGENT); }
; __device__ __forceinline__ void xcd_barrier_complete(unsigned* bar, unsigned x, unsigned& nloc, unsigned& nx) {
;     const unsigned G = gridDim.x * gridDim.y * gridDim.z;
;     unsigned sum, cnt, mine, sp = 0u;
;     for (;;) {
;         sum = 0u; cnt = 0u; mine = 0u;
; #pragma unroll
;         for (unsigned j = 0; j < 16; ++j) { const unsigned c = xb_ld(&bar[XB_XCNT(j)]); sum += c; cnt += (c > 0u) ? 1u : 0u; mine = (j == x) ? c : mine; }
; __device__ __forceinline__ void xcd_barrier(const XcdBarrier& b) {
;     asm volatile("s_waitcnt vmcnt(0)" ::: "memory");
;     __syncthreads();
;     if (threadIdx.x == 0) {
;         unsigned* bar = b.bar;
;         __builtin_amdgcn_s_waitcnt(0);
;         unsigned nloc = b.st[0], nx = b.st[1];
;         if (nloc == 0u) { xcd_barrier_complete(bar, b.x, nloc, nx); b.st[0] = nloc; b.st[1] = nx; }
.LBB0_1878:
	s_cmp_gt_i32 s29, 16
	s_cselect_b64 s[0:1], -1, 0
	s_and_b64 s[2:3], s[4:5], s[0:1]
	s_andn2_b64 vcc, exec, s[2:3]
	v_readlane_b32 s62, v243, 5
	s_cbranch_vccnz .LBB0_1928
	s_waitcnt vmcnt(0)
	v_cmp_eq_u32_e32 vcc, 0, v0
	s_waitcnt vmcnt(0) lgkmcnt(0)
	s_barrier
	v_readfirstlane_b32 s101, v0
	v_readlane_b32 s98, v244, 9
	v_readlane_b32 s99, v244, 10
	v_readlane_b32 s100, v244, 60
	s_cmp_lt_u32 s101, 64
	s_cbranch_scc1 .Lwpf_skip_14
	s_lshr_b32 s100, s100, 6
	s_mul_i32 s100, s100, 0x80000
	s_add_u32 s98, s98, 0x4100000
	s_addc_u32 s99, s99, 0
	s_add_u32 s98, s98, s100
	s_addc_u32 s99, s99, 0
	v_subrev_u32_e32 v250, 64, v0
	v_lshrrev_b32_e32 v252, 2, v250
	v_and_b32_e32 v251, 3, v250
	v_mul_u32_u24_e32 v252, 0x800, v252
	v_lshl_add_u32 v252, v251, 7, v252
	global_load_dword v253, v252, s[98:99]
	v_add_u32_e32 v251, 448, v250
	v_lshrrev_b32_e32 v252, 2, v251
	v_and_b32_e32 v251, 3, v251
	v_mul_u32_u24_e32 v252, 0x800, v252
	v_lshl_add_u32 v252, v251, 7, v252
	global_load_dword v254, v252, s[98:99]
	v_add_u32_e32 v251, 896, v250
	v_min_u32_e32 v251, 0x3ff, v251
	v_lshrrev_b32_e32 v252, 2, v251
	v_and_b32_e32 v251, 3, v251
	v_mul_u32_u24_e32 v252, 0x800, v252
	v_lshl_add_u32 v252, v251, 7, v252
	global_load_dword v255, v252, s[98:99]
.Lwpf_skip_14:
	s_and_saveexec_b64 s[4:5], vcc
	s_cbranch_execz .LBB0_1927
	v_mov_b32_e32 v1, s62
	s_waitcnt vmcnt(0) expcnt(0) lgkmcnt(0)
	ds_read_b32 v3, v1
	ds_read_b32 v1, v1 offset:4
	s_waitcnt lgkmcnt(1)
	v_cmp_ne_u32_e32 vcc, 0, v3
	s_cbranch_vccnz .LBB0_1895
	v_readlane_b32 s6, v244, 0
	v_readlane_b32 s7, v244, 1
	v_readlane_b32 s40, v244, 3
	s_load_dwordx2 s[2:3], s[6:7], 0x4
	v_readlane_b32 s46, v244, 9
	v_readlane_b32 s47, v244, 10
	s_add_u32 s6, s46, 0x4200
	s_addc_u32 s7, s47, 0
	s_add_u32 s8, s46, 0x4400
	s_addc_u32 s9, s47, 0
	v_readlane_b32 s10, v244, 2
	s_waitcnt lgkmcnt(0)
	s_mul_i32 s2, s2, s10
	s_add_u32 s10, s46, 0x4500
	s_addc_u32 s11, s47, 0
	s_add_u32 s12, s46, 0x4600
	s_addc_u32 s13, s47, 0
	s_add_u32 s14, s46, 0x4700
	s_addc_u32 s15, s47, 0
	s_add_u32 s16, s46, 0x4800
	s_addc_u32 s17, s47, 0
	s_add_u32 s18, s46, 0x4900
	s_addc_u32 s19, s47, 0
	s_add_u32 s20, s46, 0x4a00
	s_addc_u32 s21, s47, 0
	s_add_u32 s22, s46, 0x4b00
	s_addc_u32 s23, s47, 0
	s_add_u32 s24, s46, 0x4c00
	s_addc_u32 s25, s47, 0
	s_add_u32 s26, s46, 0x4d00
	s_addc_u32 s27, s47, 0
	s_add_u32 s34, s46, 0x4e00
	s_addc_u32 s35, s47, 0
	s_add_u32 s36, s46, 0x4f00
	s_addc_u32 s37, s47, 0
	s_add_u32 s38, s46, 0x5000
	s_addc_u32 s39, s47, 0
	v_readlane_b32 s41, v244, 4
	s_add_u32 s40, s46, 0x5100
	v_readlane_b32 s42, v244, 5
	s_addc_u32 s41, s47, 0
	v_readlane_b32 s43, v244, 6
	s_add_u32 s42, s46, 0x5200
	v_readlane_b32 s44, v244, 7
	s_addc_u32 s43, s47, 0
	v_readlane_b32 s45, v244, 8
	s_add_u32 s44, s46, 0x5300
	s_mul_i32 s2, s2, s3
	s_addc_u32 s45, s47, 0
	s_mov_b32 s3, 1
	v_mov_b32_e32 v17, 0
	s_branch .LBB0_1883

; __device__ __forceinline__ void xcd_barrier(const XcdBarrier& b) {
;     asm volatile("s_waitcnt vmcnt(0)" ::: "memory");
;     __syncthreads();
;     if (threadIdx.x == 0) {
.LBB0_2018:
	s_cmp_gt_i32 s29, 17
	s_cselect_b64 s[0:1], -1, 0
	s_and_b64 s[2:3], s[6:7], s[0:1]
	s_andn2_b64 vcc, exec, s[2:3]
	s_cbranch_vccnz .LBB0_2068
	s_waitcnt vmcnt(0)
	v_cmp_eq_u32_e32 vcc, 0, v0
	s_waitcnt vmcnt(0) lgkmcnt(0)
	s_barrier
	v_readfirstlane_b32 s101, v0
	v_readlane_b32 s98, v244, 9
	v_readlane_b32 s99, v244, 10
	v_readlane_b32 s100, v244, 60
	s_cmp_lt_u32 s101, 64
	s_cbranch_scc1 .Lwpf_skip_15
	s_lshr_b32 s100, s100, 6
	s_mul_i32 s100, s100, 0x80000
	s_add_u32 s98, s98, 0x1900000
	s_addc_u32 s99, s99, 0
	s_add_u32 s98, s98, s100
	s_addc_u32 s99, s99, 0
	v_subrev_u32_e32 v250, 64, v0
	v_lshrrev_b32_e32 v252, 2, v250
	v_and_b32_e32 v251, 3, v250
	v_mul_u32_u24_e32 v252, 0x800, v252
	v_lshl_add_u32 v252, v251, 7, v252
	global_load_dword v253, v252, s[98:99]
	v_add_u32_e32 v251, 448, v250
	v_lshrrev_b32_e32 v252, 2, v251
	v_and_b32_e32 v251, 3, v251
	v_mul_u32_u24_e32 v252, 0x800, v252
	v_lshl_add_u32 v252, v251, 7, v252
	global_load_dword v254, v252, s[98:99]
	v_add_u32_e32 v251, 896, v250
	v_min_u32_e32 v251, 0x3ff, v251
	v_lshrrev_b32_e32 v252, 2, v251
	v_and_b32_e32 v251, 3, v251
	v_mul_u32_u24_e32 v252, 0x800, v252
	v_lshl_add_u32 v252, v251, 7, v252
	global_load_dword v255, v252, s[98:99]

; __device__ __forceinline__ void xcd_barrier(const XcdBarrier& b) {
;     asm volatile("s_waitcnt vmcnt(0)" ::: "memory");
;     __syncthreads();
;     if (threadIdx.x == 0) {
.LBB0_2108:
	s_cmp_gt_i32 s29, 18
	s_cselect_b64 s[0:1], -1, 0
	s_and_b64 s[2:3], s[4:5], s[0:1]
	s_andn2_b64 vcc, exec, s[2:3]
	s_cbranch_vccnz .LBB0_2158
	s_waitcnt vmcnt(0)
	v_cmp_eq_u32_e32 vcc, 0, v0
	s_waitcnt vmcnt(0) lgkmcnt(0)
	s_barrier
	v_readfirstlane_b32 s101, v0
	v_readlane_b32 s98, v244, 9
	v_readlane_b32 s99, v244, 10
	v_readlane_b32 s100, v244, 60
	s_cmp_lt_u32 s101, 64
	s_cbranch_scc1 .Lwpf_skip_16
	s_lshr_b32 s100, s100, 6
	s_mul_i32 s100, s100, 0x100000
	s_add_u32 s98, s98, 0x2d00000
	s_addc_u32 s99, s99, 0
	s_add_u32 s98, s98, s100
	s_addc_u32 s99, s99, 0
	v_subrev_u32_e32 v250, 64, v0
	v_lshrrev_b32_e32 v252, 2, v250
	v_and_b32_e32 v251, 3, v250
	v_mul_u32_u24_e32 v252, 0x1000, v252
	v_lshl_add_u32 v252, v251, 7, v252
	global_load_dword v253, v252, s[98:99]
	v_add_u32_e32 v251, 448, v250
	v_lshrrev_b32_e32 v252, 2, v251
	v_and_b32_e32 v251, 3, v251
	v_mul_u32_u24_e32 v252, 0x1000, v252
	v_lshl_add_u32 v252, v251, 7, v252
	global_load_dword v254, v252, s[98:99]
	v_add_u32_e32 v251, 896, v250
	v_min_u32_e32 v251, 0x3ff, v251
	v_lshrrev_b32_e32 v252, 2, v251
	v_and_b32_e32 v251, 3, v251
	v_mul_u32_u24_e32 v252, 0x1000, v252
	v_lshl_add_u32 v252, v251, 7, v252
	global_load_dword v255, v252, s[98:99]
